# prep: p -> bf16 conversion loop keeps four 16-B loads in flight (was one load + vmcnt(0) + one store per trip)
# baseline (speedup 1.0000x reference)
.LBB0_90:
	s_mov_b32 s97, 0
	s_waitcnt vmcnt(4)
	v_mbcnt_lo_u32_b32 v2, -1, v40
	v_mbcnt_hi_u32_b32 v2, -1, v2
	v_add_u32_e32 v2, s85, v2
	s_lshl_b64 s[2:3], s[96:97], 9
	v_ashrrev_i32_e32 v3, 31, v2
	v_lshl_add_u64 v[2:3], s[2:3], 0, v[2:3]
	s_mov_b64 s[2:3], 0x400000
	v_cmp_gt_u64_e32 vcc, s[2:3], v[2:3]
	s_and_saveexec_b64 s[10:11], vcc
	s_cbranch_execz .LBB0_93
	s_load_dwordx2 s[2:3], s[4:5], 0x8
	s_mov_b32 s16, s94
	s_mov_b32 s17, s97
	s_waitcnt lgkmcnt(0)
	v_lshl_add_u64 v[4:5], v[2:3], 3, s[6:7]
	s_mov_b64 s[14:15], 0xb800000
	s_lshl_b64 s[12:13], s[16:17], 9
	v_lshl_add_u64 v[4:5], v[4:5], 0, s[14:15]
	s_lshl_b64 s[14:15], s[16:17], 12
	v_lshl_add_u64 v[6:7], v[2:3], 4, s[2:3]
	s_lshl_b64 s[16:17], s[16:17], 13
	s_mov_b64 s[18:19], 0
	s_mov_b64 s[20:21], 0x3fffff
	s_lshl_b64 s[22:23], s[12:13], 1
	s_add_u32 s22, s22, s12
	s_addc_u32 s23, s23, s13
	s_lshl_b64 s[24:25], s[12:13], 2
.Lp2b_top:
	v_cmp_ge_u64_e32 vcc, s[20:21], v[2:3]
	s_and_b64 exec, exec, vcc
	s_cbranch_execz .LBB0_93
	v_lshl_add_u64 v[216:217], v[2:3], 0, s[22:23]
	v_cmp_ge_u64_e32 vcc, s[20:21], v[216:217]
	s_cmp_eq_u64 vcc, exec
	s_cbranch_scc0 .LBB0_92
	global_load_dwordx4 v[200:203], v[6:7], off
	v_lshl_add_u64 v[6:7], v[6:7], 0, s[16:17]
	global_load_dwordx4 v[204:207], v[6:7], off
	v_lshl_add_u64 v[6:7], v[6:7], 0, s[16:17]
	global_load_dwordx4 v[208:211], v[6:7], off
	v_lshl_add_u64 v[6:7], v[6:7], 0, s[16:17]
	global_load_dwordx4 v[212:215], v[6:7], off
	v_lshl_add_u64 v[6:7], v[6:7], 0, s[16:17]
	v_lshl_add_u64 v[2:3], v[2:3], 0, s[24:25]
	s_waitcnt vmcnt(3)
	v_cvt_pk_bf16_f32 v200, v200, v201
	v_cvt_pk_bf16_f32 v201, v202, v203
	global_store_dwordx2 v[4:5], v[200:201], off
	v_lshl_add_u64 v[4:5], v[4:5], 0, s[14:15]
	s_waitcnt vmcnt(3)
	v_cvt_pk_bf16_f32 v204, v204, v205
	v_cvt_pk_bf16_f32 v205, v206, v207
	global_store_dwordx2 v[4:5], v[204:205], off
	v_lshl_add_u64 v[4:5], v[4:5], 0, s[14:15]
	s_waitcnt vmcnt(3)
	v_cvt_pk_bf16_f32 v208, v208, v209
	v_cvt_pk_bf16_f32 v209, v210, v211
	global_store_dwordx2 v[4:5], v[208:209], off
	v_lshl_add_u64 v[4:5], v[4:5], 0, s[14:15]
	s_waitcnt vmcnt(3)
	v_cvt_pk_bf16_f32 v212, v212, v213
	v_cvt_pk_bf16_f32 v213, v214, v215
	global_store_dwordx2 v[4:5], v[212:213], off
	v_lshl_add_u64 v[4:5], v[4:5], 0, s[14:15]
	s_branch .Lp2b_top
